# wave all-reduces via DPP/permlane also in the P3 token epilogue (second token)
# baseline (speedup 1.0000x reference)
; __device__ __forceinline__ void p3_dots(const u32x2 (&ur)[4], const unsigned* rec, int lane, int (&pt)[4]) {
;     const u32x4 qh = *(const u32x4*)(rec + 256 + lane * 4);
; #pragma unroll
;     for (int u = 0; u < 4; u++) {
;         const int w0 = (int)ur[u].x, w1 = (int)ur[u].y;
;         int dh = __builtin_amdgcn_sdot8(w0, (int)qh.x, 0, false);
;         dh = __builtin_amdgcn_sdot8(w1, (int)qh.z, dh, false);
;         int dl = __builtin_amdgcn_sdot8(w0, (int)qh.y, 0, false);
;         dl = __builtin_amdgcn_sdot8(w1, (int)qh.w, dl, false);
;         pt[u] = (dh << 4) + dl;
;     }
; }
; template <int CTRL> __device__ __forceinline__ int dpp_i(int v) { return __builtin_amdgcn_mov_dpp(v, CTRL, 0xF, 0xF, true); }
; __device__ __forceinline__ int xrow_sum_i(int v) {
;     const auto a = __builtin_amdgcn_permlane16_swap((unsigned)v, (unsigned)v, false, false);
;     v = (int)a[0] + (int)a[1];
;     const auto b = __builtin_amdgcn_permlane32_swap((unsigned)v, (unsigned)v, false, false);
;     return (int)b[0] + (int)b[1];
; }
; __device__ __forceinline__ float p3_weight(const int (&pt)[4], int lane, float sh, int hs8, const P3Sc& sc) {
;     int m2[2], m1;
;     const bool c0 = lane & 1;
; #pragma unroll
;     for (int j = 0; j < 2; j++) { const int keep = c0 ? pt[j + 2] : pt[j], send = c0 ? pt[j] : pt[j + 2]; m2[j] = keep + dpp_i<0xB1>(send); }
;     const bool c1 = lane & 2;
;     { const int keep = c1 ? m2[1] : m2[0], send = c1 ? m2[0] : m2[1]; m1 = keep + dpp_i<0x4E>(send); }
;     m1 += dpp_i<0x124>(m1);
;     m1 += dpp_i<0x128>(m1);
;     m1 = xrow_sum_i(m1);
;     const float aval = (float)(m1 - hs8) * sc.su;
;     return sc.gm * gelu_erf(aval);
; }
; __device__ __forceinline__ void p3_axpy(const u32x2 (&vr)[4], float ws, f32x2 (&acc)[8]) {
; #pragma unroll
;     for (int u = 0; u < 4; u++) {
;         const int la = ((u >> 1) & 1) | ((u & 1) << 1);
;         const float wu = __builtin_bit_cast(float, __builtin_amdgcn_readlane(__builtin_bit_cast(int, ws), la));
;         const f32x2 w2 = {wu, wu};
;         const unsigned vw[2] = {vr[u].x, vr[u].y};
; #pragma unroll
;         for (int i = 0; i < 2; i++) {
;             acc[i * 4 + 0] = __builtin_elementwise_fma(w2, __builtin_amdgcn_cvt_scalef32_pk_f32_fp4(vw[i], 1.0f, 0), acc[i * 4 + 0]);
.LBB0_1075:
	v_add_u32_e32 v134, s5, v121
	v_add_u32_e32 v135, s5, v137
	ds_read_b128 v[140:143], v134
	ds_read_b128 v[144:147], v134 offset:2560
	s_waitcnt vmcnt(12) lgkmcnt(2)
	v_dot8_i32_i4 v12, v80, v4, 0
	v_dot8_i32_i4 v27, v80, v5, 0
	v_dot8_i32_i4 v131, v74, v4, 0
	v_dot8_i32_i4 v132, v74, v5, 0
	v_dot8c_i32_i4_e32 v12, v81, v6
	v_dot8c_i32_i4_e32 v27, v81, v7
	v_dot8c_i32_i4_e32 v131, v75, v6
	v_dot8c_i32_i4_e32 v132, v75, v7
	v_dot8_i32_i4 v133, v84, v4, 0
	v_dot8_i32_i4 v176, v84, v5, 0
	v_dot8_i32_i4 v177, v82, v4, 0
	v_dot8_i32_i4 v178, v82, v5, 0
	v_dot8c_i32_i4_e32 v133, v85, v6
	v_dot8c_i32_i4_e32 v176, v85, v7
	v_dot8c_i32_i4_e32 v177, v83, v6
	v_dot8c_i32_i4_e32 v178, v83, v7
	v_lshl_add_u32 v27, v12, 4, v27
	v_lshl_add_u32 v131, v131, 4, v132
	v_lshl_add_u32 v132, v133, 4, v176
	v_lshl_add_u32 v133, v177, 4, v178
	v_cndmask_b32_e64 v12, v132, v27, s[0:1]
	v_cndmask_b32_e64 v27, v27, v132, s[0:1]
	s_waitcnt lgkmcnt(0)
	v_lshl_add_u32 v140, v140, 9, v136
	v_add_u32_dpp v12, v27, v12 quad_perm:[1,0,3,2] row_mask:0xf bank_mask:0xf bound_ctrl:1
	v_cndmask_b32_e64 v27, v133, v131, s[0:1]
	v_cndmask_b32_e64 v131, v131, v133, s[0:1]
	v_lshl_add_u32 v141, v141, 9, v136
	v_lshl_add_u32 v142, v142, 9, v136
	v_add_u32_dpp v27, v131, v27 quad_perm:[1,0,3,2] row_mask:0xf bank_mask:0xf bound_ctrl:1
	v_cndmask_b32_e64 v131, v27, v12, s[2:3]
	v_cndmask_b32_e64 v12, v12, v27, s[2:3]
	v_lshl_add_u32 v143, v143, 9, v136
	global_load_dwordx2 v[80:81], v140, s[50:51]
	v_add_u32_dpp v12, v12, v131 quad_perm:[2,3,0,1] row_mask:0xf bank_mask:0xf bound_ctrl:1
	global_load_dwordx2 v[74:75], v141, s[50:51]
	global_load_dwordx2 v[84:85], v142, s[50:51]
	v_add_u32_dpp v12, v12, v12 row_ror:4 row_mask:0xf bank_mask:0xf bound_ctrl:1
	global_load_dwordx2 v[82:83], v143, s[50:51]
	s_waitcnt vmcnt(8)
	v_add_u32_dpp v181, v12, v12 row_ror:8 row_mask:0xf bank_mask:0xf bound_ctrl:1
	v_dot8_i32_i4 v12, v66, v0, 0
	v_dot8_i32_i4 v27, v66, v1, 0
	v_dot8_i32_i4 v131, v60, v0, 0
	v_dot8_i32_i4 v132, v60, v1, 0
	v_dot8c_i32_i4_e32 v12, v67, v2
	v_dot8c_i32_i4_e32 v27, v67, v3
	v_dot8c_i32_i4_e32 v131, v61, v2
	v_dot8c_i32_i4_e32 v132, v61, v3
	v_dot8_i32_i4 v133, v68, v0, 0
	v_dot8_i32_i4 v176, v68, v1, 0
	v_dot8_i32_i4 v177, v64, v0, 0
	v_dot8_i32_i4 v178, v64, v1, 0
	v_dot8c_i32_i4_e32 v133, v69, v2
	v_dot8c_i32_i4_e32 v176, v69, v3
	v_dot8c_i32_i4_e32 v177, v65, v2
	v_dot8c_i32_i4_e32 v178, v65, v3
	v_lshl_add_u32 v27, v12, 4, v27
	v_lshl_add_u32 v131, v131, 4, v132
	v_lshl_add_u32 v132, v133, 4, v176
	v_lshl_add_u32 v133, v177, 4, v178
	v_cndmask_b32_e64 v12, v132, v27, s[0:1]
	v_cndmask_b32_e64 v27, v27, v132, s[0:1]
	v_lshl_add_u32 v144, v144, 9, v136
	v_lshl_add_u32 v145, v145, 9, v136
	v_add_u32_dpp v12, v27, v12 quad_perm:[1,0,3,2] row_mask:0xf bank_mask:0xf bound_ctrl:1
	v_cndmask_b32_e64 v27, v133, v131, s[0:1]
	v_cndmask_b32_e64 v131, v131, v133, s[0:1]
	v_lshl_add_u32 v146, v146, 9, v136
	v_lshl_add_u32 v147, v147, 9, v136
	v_add_u32_dpp v27, v131, v27 quad_perm:[1,0,3,2] row_mask:0xf bank_mask:0xf bound_ctrl:1
	v_cndmask_b32_e64 v131, v27, v12, s[2:3]
	v_cndmask_b32_e64 v12, v12, v27, s[2:3]
	global_load_dwordx2 v[66:67], v144, s[50:51]
	global_load_dwordx2 v[60:61], v145, s[50:51]
	v_add_u32_dpp v12, v12, v131 quad_perm:[2,3,0,1] row_mask:0xf bank_mask:0xf bound_ctrl:1
	global_load_dwordx2 v[68:69], v146, s[50:51]
	global_load_dwordx2 v[64:65], v147, s[50:51]
	v_add_u32_dpp v12, v12, v12 row_ror:4 row_mask:0xf bank_mask:0xf bound_ctrl:1
	v_cvt_scalef32_pk_f32_fp4 v[160:161], v72, 1.0
	v_cvt_scalef32_pk_f32_fp4 v[162:163], v72, 1.0 op_sel:[1,0,0]
	v_add_u32_dpp v12, v12, v12 row_ror:8 row_mask:0xf bank_mask:0xf bound_ctrl:1
	v_cvt_scalef32_pk_f32_fp4 v[164:165], v72, 1.0 op_sel:[0,1,0]
	v_cvt_scalef32_pk_f32_fp4 v[166:167], v72, 1.0 op_sel:[1,1,0]
	v_permlane16_swap_b32_e32 v181, v12
	v_add_u32_e32 v12, v181, v12
	v_mov_b32_e32 v27, v12
	v_cvt_scalef32_pk_f32_fp4 v[168:169], v73, 1.0
	v_cvt_scalef32_pk_f32_fp4 v[170:171], v73, 1.0 op_sel:[1,0,0]
	v_permlane32_swap_b32_e32 v12, v27
	v_add_u32_e32 v12, v27, v12
	v_cvt_f32_i32_e32 v12, v12
	v_mul_f32_e32 v12, v77, v12
	v_fma_f32 v179, |v12|, s39, 1.0
	v_rcp_f32_e32 v179, v179
	v_cmp_gt_f32_e32 vcc, 0, v12
	v_fmamk_f32 v180, v179, 0x3f07dc22, v129
	v_fmaak_f32 v180, v179, v180, 0x3f35f0e3
	v_fmaak_f32 v180, v179, v180, 0xbe11a98e
	v_fmaak_f32 v180, v179, v180, 0x3e027906
	v_mul_f32_e32 v179, v179, v180
	v_mul_f32_e32 v180, v12, v12
	v_mul_f32_e32 v180, 0xbf38aa3b, v180
	v_exp_f32_e32 v180, v180
	v_cvt_scalef32_pk_f32_fp4 v[172:173], v73, 1.0 op_sel:[0,1,0]
	v_mul_f32_e32 v179, v180, v179
	v_mul_f32_e32 v180, v12, v179
	v_fma_f32 v12, -v12, v179, v12
	v_cndmask_b32_e32 v12, v12, v180, vcc
	v_mul_f32_e32 v12, v76, v12
	ds_read2st64_b32 v[76:77], v135 offset1:6
	v_readlane_b32 s4, v12, 0
	v_cvt_scalef32_pk_f32_fp4 v[174:175], v73, 1.0 op_sel:[1,1,0]
	global_load_dwordx2 v[72:73], v140, s[52:53]
	v_pk_fma_f32 v[100:101], s[4:5], v[160:161], v[100:101] op_sel_hi:[0,1,1]
	v_pk_fma_f32 v[98:99], s[4:5], v[162:163], v[98:99] op_sel_hi:[0,1,1]
	v_pk_fma_f32 v[96:97], s[4:5], v[164:165], v[96:97] op_sel_hi:[0,1,1]
	v_pk_fma_f32 v[94:95], s[4:5], v[166:167], v[94:95] op_sel_hi:[0,1,1]
	v_pk_fma_f32 v[92:93], s[4:5], v[168:169], v[92:93] op_sel_hi:[0,1,1]
	v_pk_fma_f32 v[90:91], s[4:5], v[170:171], v[90:91] op_sel_hi:[0,1,1]
	v_pk_fma_f32 v[88:89], s[4:5], v[172:173], v[88:89] op_sel_hi:[0,1,1]
	v_pk_fma_f32 v[86:87], s[4:5], v[174:175], v[86:87] op_sel_hi:[0,1,1]
	v_readlane_b32 s4, v12, 2
	v_cvt_scalef32_pk_f32_fp4 v[160:161], v70, 1.0
	v_cvt_scalef32_pk_f32_fp4 v[162:163], v70, 1.0 op_sel:[1,0,0]
; __device__ __forceinline__ void p3_load_v(u32x2 (&vr)[4], const unsigned char* __restrict__ VQ, int lane, int g, const unsigned* rec) {
; #pragma unroll
;     for (int u = 0; u < 4; u++) vr[u] = *(const u32x2*)(VQ + (size_t)rec[4 * g + u] * 512 + lane * 8);
; }
; __device__ __forceinline__ void p3_axpy(const u32x2 (&vr)[4], float ws, f32x2 (&acc)[8]) {
; #pragma unroll
;     for (int u = 0; u < 4; u++) {
;         const int la = ((u >> 1) & 1) | ((u & 1) << 1);
;         const float wu = __builtin_bit_cast(float, __builtin_amdgcn_readlane(__builtin_bit_cast(int, ws), la));
;         const f32x2 w2 = {wu, wu};
;         const unsigned vw[2] = {vr[u].x, vr[u].y};
; #pragma unroll
;         for (int i = 0; i < 2; i++) {
;             acc[i * 4 + 0] = __builtin_elementwise_fma(w2, __builtin_amdgcn_cvt_scalef32_pk_f32_fp4(vw[i], 1.0f, 0), acc[i * 4 + 0]);
;             acc[i * 4 + 1] = __builtin_elementwise_fma(w2, __builtin_amdgcn_cvt_scalef32_pk_f32_fp4(vw[i], 1.0f, 1), acc[i * 4 + 1]);
;             acc[i * 4 + 2] = __builtin_elementwise_fma(w2, __builtin_amdgcn_cvt_scalef32_pk_f32_fp4(vw[i], 1.0f, 2), acc[i * 4 + 2]);
;             acc[i * 4 + 3] = __builtin_elementwise_fma(w2, __builtin_amdgcn_cvt_scalef32_pk_f32_fp4(vw[i], 1.0f, 3), acc[i * 4 + 3]);
;         }
;     }
; }
	v_pk_fma_f32 v[100:101], s[4:5], v[160:161], v[100:101] op_sel_hi:[0,1,1]
	v_cvt_scalef32_pk_f32_fp4 v[164:165], v70, 1.0 op_sel:[0,1,0]
	v_pk_fma_f32 v[98:99], s[4:5], v[162:163], v[98:99] op_sel_hi:[0,1,1]
	v_cvt_scalef32_pk_f32_fp4 v[166:167], v70, 1.0 op_sel:[1,1,0]
	v_pk_fma_f32 v[96:97], s[4:5], v[164:165], v[96:97] op_sel_hi:[0,1,1]
	v_cvt_scalef32_pk_f32_fp4 v[168:169], v71, 1.0
	v_pk_fma_f32 v[94:95], s[4:5], v[166:167], v[94:95] op_sel_hi:[0,1,1]
	v_cvt_scalef32_pk_f32_fp4 v[170:171], v71, 1.0 op_sel:[1,0,0]
	v_pk_fma_f32 v[92:93], s[4:5], v[168:169], v[92:93] op_sel_hi:[0,1,1]
	v_cvt_scalef32_pk_f32_fp4 v[172:173], v71, 1.0 op_sel:[0,1,0]
	v_pk_fma_f32 v[90:91], s[4:5], v[170:171], v[90:91] op_sel_hi:[0,1,1]
	v_cvt_scalef32_pk_f32_fp4 v[174:175], v71, 1.0 op_sel:[1,1,0]
	v_pk_fma_f32 v[88:89], s[4:5], v[172:173], v[88:89] op_sel_hi:[0,1,1]
	v_pk_fma_f32 v[86:87], s[4:5], v[174:175], v[86:87] op_sel_hi:[0,1,1]
	global_load_dwordx2 v[70:71], v141, s[52:53]
	v_readlane_b32 s4, v12, 1
	v_cvt_scalef32_pk_f32_fp4 v[160:161], v62, 1.0
	v_cvt_scalef32_pk_f32_fp4 v[162:163], v62, 1.0 op_sel:[1,0,0]
	v_pk_fma_f32 v[100:101], s[4:5], v[160:161], v[100:101] op_sel_hi:[0,1,1]
	v_cvt_scalef32_pk_f32_fp4 v[164:165], v62, 1.0 op_sel:[0,1,0]
	v_pk_fma_f32 v[98:99], s[4:5], v[162:163], v[98:99] op_sel_hi:[0,1,1]
	v_cvt_scalef32_pk_f32_fp4 v[166:167], v62, 1.0 op_sel:[1,1,0]
	v_pk_fma_f32 v[96:97], s[4:5], v[164:165], v[96:97] op_sel_hi:[0,1,1]
	v_cvt_scalef32_pk_f32_fp4 v[168:169], v63, 1.0
	v_pk_fma_f32 v[94:95], s[4:5], v[166:167], v[94:95] op_sel_hi:[0,1,1]
	v_cvt_scalef32_pk_f32_fp4 v[170:171], v63, 1.0 op_sel:[1,0,0]
	v_pk_fma_f32 v[92:93], s[4:5], v[168:169], v[92:93] op_sel_hi:[0,1,1]
	v_cvt_scalef32_pk_f32_fp4 v[172:173], v63, 1.0 op_sel:[0,1,0]
	v_pk_fma_f32 v[90:91], s[4:5], v[170:171], v[90:91] op_sel_hi:[0,1,1]
	v_cvt_scalef32_pk_f32_fp4 v[174:175], v63, 1.0 op_sel:[1,1,0]
	v_pk_fma_f32 v[88:89], s[4:5], v[172:173], v[88:89] op_sel_hi:[0,1,1]
	v_pk_fma_f32 v[86:87], s[4:5], v[174:175], v[86:87] op_sel_hi:[0,1,1]
	global_load_dwordx2 v[62:63], v142, s[52:53]
	v_readlane_b32 s4, v12, 3
	v_cvt_scalef32_pk_f32_fp4 v[160:161], v58, 1.0
	v_cvt_scalef32_pk_f32_fp4 v[162:163], v58, 1.0 op_sel:[1,0,0]
	v_pk_fma_f32 v[100:101], s[4:5], v[160:161], v[100:101] op_sel_hi:[0,1,1]
	v_cvt_scalef32_pk_f32_fp4 v[164:165], v58, 1.0 op_sel:[0,1,0]
	v_pk_fma_f32 v[98:99], s[4:5], v[162:163], v[98:99] op_sel_hi:[0,1,1]
	v_cvt_scalef32_pk_f32_fp4 v[166:167], v58, 1.0 op_sel:[1,1,0]
	v_pk_fma_f32 v[96:97], s[4:5], v[164:165], v[96:97] op_sel_hi:[0,1,1]
	v_cvt_scalef32_pk_f32_fp4 v[168:169], v59, 1.0
	v_pk_fma_f32 v[94:95], s[4:5], v[166:167], v[94:95] op_sel_hi:[0,1,1]
	v_cvt_scalef32_pk_f32_fp4 v[170:171], v59, 1.0 op_sel:[1,0,0]
	v_pk_fma_f32 v[92:93], s[4:5], v[168:169], v[92:93] op_sel_hi:[0,1,1]
	v_cvt_scalef32_pk_f32_fp4 v[172:173], v59, 1.0 op_sel:[0,1,0]
	v_pk_fma_f32 v[90:91], s[4:5], v[170:171], v[90:91] op_sel_hi:[0,1,1]
	v_cvt_scalef32_pk_f32_fp4 v[174:175], v59, 1.0 op_sel:[1,1,0]
	v_pk_fma_f32 v[88:89], s[4:5], v[172:173], v[88:89] op_sel_hi:[0,1,1]
	v_pk_fma_f32 v[86:87], s[4:5], v[174:175], v[86:87] op_sel_hi:[0,1,1]
	global_load_dwordx2 v[58:59], v143, s[52:53]
	s_waitcnt vmcnt(15)
	v_readlane_b32 s4, v12, 16
	v_cvt_scalef32_pk_f32_fp4 v[160:161], v40, 1.0
	v_cvt_scalef32_pk_f32_fp4 v[162:163], v40, 1.0 op_sel:[1,0,0]
	v_pk_fma_f32 v[52:53], s[4:5], v[160:161], v[52:53] op_sel_hi:[0,1,1]
	v_cvt_scalef32_pk_f32_fp4 v[164:165], v40, 1.0 op_sel:[0,1,0]
	v_pk_fma_f32 v[50:51], s[4:5], v[162:163], v[50:51] op_sel_hi:[0,1,1]
	v_cvt_scalef32_pk_f32_fp4 v[166:167], v40, 1.0 op_sel:[1,1,0]
	v_pk_fma_f32 v[48:49], s[4:5], v[164:165], v[48:49] op_sel_hi:[0,1,1]
	v_cvt_scalef32_pk_f32_fp4 v[168:169], v41, 1.0
	v_pk_fma_f32 v[46:47], s[4:5], v[166:167], v[46:47] op_sel_hi:[0,1,1]
	v_cvt_scalef32_pk_f32_fp4 v[170:171], v41, 1.0 op_sel:[1,0,0]
	v_pk_fma_f32 v[44:45], s[4:5], v[168:169], v[44:45] op_sel_hi:[0,1,1]
	v_cvt_scalef32_pk_f32_fp4 v[172:173], v41, 1.0 op_sel:[0,1,0]
	v_pk_fma_f32 v[42:43], s[4:5], v[170:171], v[42:43] op_sel_hi:[0,1,1]
	v_cvt_scalef32_pk_f32_fp4 v[174:175], v41, 1.0 op_sel:[1,1,0]
	v_pk_fma_f32 v[54:55], s[4:5], v[172:173], v[54:55] op_sel_hi:[0,1,1]
	v_pk_fma_f32 v[56:57], s[4:5], v[174:175], v[56:57] op_sel_hi:[0,1,1]
	global_load_dwordx2 v[40:41], v144, s[52:53]
	s_waitcnt vmcnt(15)
	v_readlane_b32 s4, v12, 18
	v_cvt_scalef32_pk_f32_fp4 v[160:161], v38, 1.0
	v_cvt_scalef32_pk_f32_fp4 v[162:163], v38, 1.0 op_sel:[1,0,0]
	v_pk_fma_f32 v[52:53], s[4:5], v[160:161], v[52:53] op_sel_hi:[0,1,1]
	v_cvt_scalef32_pk_f32_fp4 v[164:165], v38, 1.0 op_sel:[0,1,0]
	v_pk_fma_f32 v[50:51], s[4:5], v[162:163], v[50:51] op_sel_hi:[0,1,1]
	v_cvt_scalef32_pk_f32_fp4 v[166:167], v38, 1.0 op_sel:[1,1,0]
	v_pk_fma_f32 v[48:49], s[4:5], v[164:165], v[48:49] op_sel_hi:[0,1,1]
	v_cvt_scalef32_pk_f32_fp4 v[168:169], v39, 1.0
	v_pk_fma_f32 v[46:47], s[4:5], v[166:167], v[46:47] op_sel_hi:[0,1,1]
	v_cvt_scalef32_pk_f32_fp4 v[170:171], v39, 1.0 op_sel:[1,0,0]
	v_pk_fma_f32 v[44:45], s[4:5], v[168:169], v[44:45] op_sel_hi:[0,1,1]
	v_cvt_scalef32_pk_f32_fp4 v[172:173], v39, 1.0 op_sel:[0,1,0]
	v_pk_fma_f32 v[42:43], s[4:5], v[170:171], v[42:43] op_sel_hi:[0,1,1]
	v_cvt_scalef32_pk_f32_fp4 v[174:175], v39, 1.0 op_sel:[1,1,0]
	v_pk_fma_f32 v[54:55], s[4:5], v[172:173], v[54:55] op_sel_hi:[0,1,1]
	v_pk_fma_f32 v[56:57], s[4:5], v[174:175], v[56:57] op_sel_hi:[0,1,1]
	global_load_dwordx2 v[38:39], v145, s[52:53]
	s_waitcnt vmcnt(15)
; __device__ __forceinline__ void p3_dots(const u32x2 (&ur)[4], const unsigned* rec, int lane, int (&pt)[4]) {
;     const u32x4 qh = *(const u32x4*)(rec + 256 + lane * 4);
; #pragma unroll
;     for (int u = 0; u < 4; u++) {
;         const int w0 = (int)ur[u].x, w1 = (int)ur[u].y;
;         int dh = __builtin_amdgcn_sdot8(w0, (int)qh.x, 0, false);
;         dh = __builtin_amdgcn_sdot8(w1, (int)qh.z, dh, false);
;         int dl = __builtin_amdgcn_sdot8(w0, (int)qh.y, 0, false);
;         dl = __builtin_amdgcn_sdot8(w1, (int)qh.w, dl, false);
;         pt[u] = (dh << 4) + dl;
;     }
; }
; template <int CTRL> __device__ __forceinline__ int dpp_i(int v) { return __builtin_amdgcn_mov_dpp(v, CTRL, 0xF, 0xF, true); }
; __device__ __forceinline__ int xrow_sum_i(int v) {
;     const auto a = __builtin_amdgcn_permlane16_swap((unsigned)v, (unsigned)v, false, false);
;     v = (int)a[0] + (int)a[1];
;     const auto b = __builtin_amdgcn_permlane32_swap((unsigned)v, (unsigned)v, false, false);
;     return (int)b[0] + (int)b[1];
; }
; __device__ __forceinline__ float p3_weight(const int (&pt)[4], int lane, float sh, int hs8, const P3Sc& sc) {
;     int m2[2], m1;
;     const bool c0 = lane & 1;
; #pragma unroll
;     for (int j = 0; j < 2; j++) { const int keep = c0 ? pt[j + 2] : pt[j], send = c0 ? pt[j] : pt[j + 2]; m2[j] = keep + dpp_i<0xB1>(send); }
; __device__ __forceinline__ void p3_axpy(const u32x2 (&vr)[4], float ws, f32x2 (&acc)[8]) {
; #pragma unroll
;     for (int u = 0; u < 4; u++) {
;         const int la = ((u >> 1) & 1) | ((u & 1) << 1);
;         const float wu = __builtin_bit_cast(float, __builtin_amdgcn_readlane(__builtin_bit_cast(int, ws), la));
;         const f32x2 w2 = {wu, wu};
;         const unsigned vw[2] = {vr[u].x, vr[u].y};
; #pragma unroll
;         for (int i = 0; i < 2; i++) {
;             acc[i * 4 + 0] = __builtin_elementwise_fma(w2, __builtin_amdgcn_cvt_scalef32_pk_f32_fp4(vw[i], 1.0f, 0), acc[i * 4 + 0]);
;             acc[i * 4 + 1] = __builtin_elementwise_fma(w2, __builtin_amdgcn_cvt_scalef32_pk_f32_fp4(vw[i], 1.0f, 1), acc[i * 4 + 1]);
;             acc[i * 4 + 2] = __builtin_elementwise_fma(w2, __builtin_amdgcn_cvt_scalef32_pk_f32_fp4(vw[i], 1.0f, 2), acc[i * 4 + 2]);
;             acc[i * 4 + 3] = __builtin_elementwise_fma(w2, __builtin_amdgcn_cvt_scalef32_pk_f32_fp4(vw[i], 1.0f, 3), acc[i * 4 + 3]);
;         }
;     }
; }
	v_readlane_b32 s4, v12, 17
	v_cvt_scalef32_pk_f32_fp4 v[160:161], v36, 1.0
	v_cvt_scalef32_pk_f32_fp4 v[162:163], v36, 1.0 op_sel:[1,0,0]
	v_pk_fma_f32 v[52:53], s[4:5], v[160:161], v[52:53] op_sel_hi:[0,1,1]
	v_cvt_scalef32_pk_f32_fp4 v[164:165], v36, 1.0 op_sel:[0,1,0]
	v_pk_fma_f32 v[50:51], s[4:5], v[162:163], v[50:51] op_sel_hi:[0,1,1]
	v_cvt_scalef32_pk_f32_fp4 v[166:167], v36, 1.0 op_sel:[1,1,0]
	v_pk_fma_f32 v[48:49], s[4:5], v[164:165], v[48:49] op_sel_hi:[0,1,1]
	v_cvt_scalef32_pk_f32_fp4 v[168:169], v37, 1.0
	v_pk_fma_f32 v[46:47], s[4:5], v[166:167], v[46:47] op_sel_hi:[0,1,1]
	v_cvt_scalef32_pk_f32_fp4 v[170:171], v37, 1.0 op_sel:[1,0,0]
	v_pk_fma_f32 v[44:45], s[4:5], v[168:169], v[44:45] op_sel_hi:[0,1,1]
	v_cvt_scalef32_pk_f32_fp4 v[172:173], v37, 1.0 op_sel:[0,1,0]
	v_pk_fma_f32 v[42:43], s[4:5], v[170:171], v[42:43] op_sel_hi:[0,1,1]
	v_cvt_scalef32_pk_f32_fp4 v[174:175], v37, 1.0 op_sel:[1,1,0]
	v_pk_fma_f32 v[54:55], s[4:5], v[172:173], v[54:55] op_sel_hi:[0,1,1]
	v_pk_fma_f32 v[56:57], s[4:5], v[174:175], v[56:57] op_sel_hi:[0,1,1]
	global_load_dwordx2 v[36:37], v146, s[52:53]
	s_waitcnt vmcnt(15)
	v_readlane_b32 s4, v12, 19
	v_cvt_scalef32_pk_f32_fp4 v[160:161], v34, 1.0
	v_cvt_scalef32_pk_f32_fp4 v[162:163], v34, 1.0 op_sel:[1,0,0]
	v_pk_fma_f32 v[52:53], s[4:5], v[160:161], v[52:53] op_sel_hi:[0,1,1]
	v_cvt_scalef32_pk_f32_fp4 v[164:165], v34, 1.0 op_sel:[0,1,0]
	v_pk_fma_f32 v[50:51], s[4:5], v[162:163], v[50:51] op_sel_hi:[0,1,1]
	v_cvt_scalef32_pk_f32_fp4 v[166:167], v34, 1.0 op_sel:[1,1,0]
	v_pk_fma_f32 v[48:49], s[4:5], v[164:165], v[48:49] op_sel_hi:[0,1,1]
	v_cvt_scalef32_pk_f32_fp4 v[168:169], v35, 1.0
	v_pk_fma_f32 v[46:47], s[4:5], v[166:167], v[46:47] op_sel_hi:[0,1,1]
	v_cvt_scalef32_pk_f32_fp4 v[170:171], v35, 1.0 op_sel:[1,0,0]
	v_pk_fma_f32 v[44:45], s[4:5], v[168:169], v[44:45] op_sel_hi:[0,1,1]
	v_cvt_scalef32_pk_f32_fp4 v[172:173], v35, 1.0 op_sel:[0,1,0]
	v_pk_fma_f32 v[42:43], s[4:5], v[170:171], v[42:43] op_sel_hi:[0,1,1]
	v_cvt_scalef32_pk_f32_fp4 v[174:175], v35, 1.0 op_sel:[1,1,0]
	v_pk_fma_f32 v[54:55], s[4:5], v[172:173], v[54:55] op_sel_hi:[0,1,1]
	v_pk_fma_f32 v[56:57], s[4:5], v[174:175], v[56:57] op_sel_hi:[0,1,1]
	global_load_dwordx2 v[34:35], v147, s[52:53]
	s_add_i32 s5, s5, 16
	s_cmpk_eq_i32 s5, 0x1f0
	s_cbranch_scc0 .LBB0_1075
	v_add_u32_e32 v135, 0x1e0, v120
	ds_read2st64_b32 v[104:105], v135 offset1:6
	ds_read2st64_b32 v[102:103], v135 offset0:10 offset1:16
	s_waitcnt vmcnt(0) lgkmcnt(0)
	v_mov_b32_e32 v12, v13
	v_mov_b32_e32 v27, v13
	s_waitcnt vmcnt(8)
	v_dot8c_i32_i4_e32 v12, v82, v4
	v_dot8c_i32_i4_e32 v27, v82, v5
	v_dot8c_i32_i4_e32 v12, v83, v6
	v_dot8c_i32_i4_e32 v27, v83, v7
	v_mov_b32_e32 v76, v13
	v_dot8c_i32_i4_e32 v76, v84, v5
	v_dot8c_i32_i4_e32 v76, v85, v7
	v_lshl_add_u32 v12, v12, 4, v27
	v_mov_b32_e32 v27, v13
	v_dot8c_i32_i4_e32 v27, v84, v4
	v_dot8c_i32_i4_e32 v27, v85, v6
	v_mov_b32_e32 v77, v13
	v_dot8c_i32_i4_e32 v77, v74, v5
	v_dot8c_i32_i4_e32 v77, v75, v7
	v_lshl_add_u32 v27, v27, 4, v76
	v_mov_b32_e32 v76, v13
	v_dot8c_i32_i4_e32 v76, v74, v4
	v_dot8c_i32_i4_e32 v76, v75, v6
	v_mov_b32_e32 v75, v13
	v_dot8c_i32_i4_e32 v75, v80, v4
	v_mov_b32_e32 v4, v13
	v_dot8c_i32_i4_e32 v4, v80, v5
	v_dot8c_i32_i4_e32 v75, v81, v6
	v_dot8c_i32_i4_e32 v4, v81, v7
	v_lshl_add_u32 v74, v76, 4, v77
	v_cndmask_b32_e64 v6, v74, v12, s[0:1]
	v_cvt_scalef32_pk_f32_fp4 v[76:77], v72, 1.0 op_sel:[1,1,0]
	v_lshl_add_u32 v4, v75, 4, v4
	v_cndmask_b32_e64 v5, v27, v4, s[0:1]
	v_cndmask_b32_e64 v4, v4, v27, s[0:1]
	v_cvt_scalef32_pk_f32_fp4 v[78:79], v73, 1.0
	v_cvt_scalef32_pk_f32_fp4 v[80:81], v73, 1.0 op_sel:[1,0,0]
	v_add_u32_dpp v4, v4, v5 quad_perm:[1,0,3,2] row_mask:0xf bank_mask:0xf bound_ctrl:1
	v_cndmask_b32_e64 v5, v12, v74, s[0:1]
	v_cvt_scalef32_pk_f32_fp4 v[74:75], v72, 1.0 op_sel:[0,1,0]
	v_cvt_scalef32_pk_f32_fp4 v[82:83], v73, 1.0 op_sel:[0,1,0]
	v_add_u32_dpp v5, v6, v5 quad_perm:[1,0,3,2] row_mask:0xf bank_mask:0xf bound_ctrl:1
	v_cndmask_b32_e64 v6, v5, v4, s[2:3]
	v_cndmask_b32_e64 v4, v4, v5, s[2:3]
	v_cvt_scalef32_pk_f32_fp4 v[84:85], v70, 1.0
	v_lshl_add_u64 v[28:29], v[22:23], 0, v[28:29]
	v_add_u32_dpp v4, v4, v6 quad_perm:[2,3,0,1] row_mask:0xf bank_mask:0xf bound_ctrl:1
	v_mov_b32_e32 v27, v13
	v_cvt_scalef32_pk_f32_fp4 v[108:109], v62, 1.0 op_sel:[0,1,0]
	v_add_u32_dpp v4, v4, v4 row_ror:4 row_mask:0xf bank_mask:0xf bound_ctrl:1
	s_nop 1
	v_add_u32_dpp v4, v4, v4 row_ror:8 row_mask:0xf bank_mask:0xf bound_ctrl:1
	v_mov_b32_e32 v5, v4
	s_nop 1
	v_permlane16_swap_b32_e32 v4, v5
	v_add_u32_e32 v4, v4, v5
	v_mov_b32_e32 v5, v4
	s_nop 1
	v_permlane32_swap_b32_e32 v4, v5
	v_add_u32_e32 v4, v5, v4
	v_cvt_f32_i32_e32 v4, v4
	v_mul_f32_e32 v4, v105, v4
	v_fma_f32 v5, |v4|, s39, 1.0
	v_rcp_f32_e32 v5, v5
	v_mul_f32_e32 v7, v4, v4
	v_mul_f32_e32 v7, 0xbf38aa3b, v7
	v_exp_f32_e32 v7, v7
	v_fmamk_f32 v6, v5, 0x3f07dc22, v129
	v_fmaak_f32 v6, v5, v6, 0x3f35f0e3
	v_fmaak_f32 v6, v5, v6, 0xbe11a98e
	v_fmaak_f32 v6, v5, v6, 0x3e027906
	v_mul_f32_e32 v5, v5, v6
	v_mul_f32_e32 v5, v7, v5
	v_mul_f32_e32 v6, v4, v5
	v_fma_f32 v5, -v4, v5, v4
	v_cmp_gt_f32_e32 vcc, 0, v4
	s_nop 1
	v_cndmask_b32_e32 v4, v5, v6, vcc
	v_mul_f32_e32 v12, v104, v4
	v_cvt_scalef32_pk_f32_fp4 v[4:5], v72, 1.0
	v_readlane_b32 s4, v12, 0
	v_cvt_scalef32_pk_f32_fp4 v[6:7], v72, 1.0 op_sel:[1,0,0]
	v_cvt_scalef32_pk_f32_fp4 v[72:73], v73, 1.0 op_sel:[1,1,0]
	v_pk_fma_f32 v[4:5], s[4:5], v[4:5], v[100:101] op_sel_hi:[0,1,1]
	v_pk_fma_f32 v[6:7], s[4:5], v[6:7], v[98:99] op_sel_hi:[0,1,1]
	v_pk_fma_f32 v[74:75], s[4:5], v[74:75], v[96:97] op_sel_hi:[0,1,1]
	v_pk_fma_f32 v[76:77], s[4:5], v[76:77], v[94:95] op_sel_hi:[0,1,1]
; __device__ __forceinline__ float bf_lo(unsigned u) { return __uint_as_float(u << 16); }
; __device__ __forceinline__ float bf_hi(unsigned u) { return __uint_as_float(u & 0xffff0000u); }
; __device__ __forceinline__ void p3_axpy(const u32x2 (&vr)[4], float ws, f32x2 (&acc)[8]) {
; #pragma unroll
;     for (int u = 0; u < 4; u++) {
;         const int la = ((u >> 1) & 1) | ((u & 1) << 1);
;         const float wu = __builtin_bit_cast(float, __builtin_amdgcn_readlane(__builtin_bit_cast(int, ws), la));
;         const f32x2 w2 = {wu, wu};
;         const unsigned vw[2] = {vr[u].x, vr[u].y};
; #pragma unroll
;         for (int i = 0; i < 2; i++) {
;             acc[i * 4 + 0] = __builtin_elementwise_fma(w2, __builtin_amdgcn_cvt_scalef32_pk_f32_fp4(vw[i], 1.0f, 0), acc[i * 4 + 0]);
;             acc[i * 4 + 1] = __builtin_elementwise_fma(w2, __builtin_amdgcn_cvt_scalef32_pk_f32_fp4(vw[i], 1.0f, 1), acc[i * 4 + 1]);
;             acc[i * 4 + 2] = __builtin_elementwise_fma(w2, __builtin_amdgcn_cvt_scalef32_pk_f32_fp4(vw[i], 1.0f, 2), acc[i * 4 + 2]);
;             acc[i * 4 + 3] = __builtin_elementwise_fma(w2, __builtin_amdgcn_cvt_scalef32_pk_f32_fp4(vw[i], 1.0f, 3), acc[i * 4 + 3]);
;         }
;     }
; }
; __device__ __forceinline__ void p3_finish(const Params& p, float* dstp, int tok, int lane, const f32x2 (&acc)[8], float* tr) {
;     ...
;     const bf16_t* x1b = (const bf16_t*)(p.ws + OFF_X1B) + (size_t)tok * DM + d0;
;     const u32x4 xa = *(const u32x4*)x1b, xb = *(const u32x4*)(x1b + 8);
;     const unsigned xw[8] = {xa.x, xa.y, xa.z, xa.w, xb.x, xb.y, xb.z, xb.w};
; #pragma unroll
;     for (int i = 0; i < 4; i++) {
;         const int d = d0 + i * 4;
;         const f32x4 xv = {bf_lo(xw[2 * i]), bf_hi(xw[2 * i]), bf_lo(xw[2 * i + 1]), bf_hi(xw[2 * i + 1])};
;         const f32x4 gt = *(const f32x4*)(mod + b * 6144 + 5 * 1024 + d);
; #pragma unroll
;         for (int j = 0; j < 4; j++) { const float v = xv[j] + gt[j] * own[i * 4 + j]; x2[i * 4 + j] = v; ss += v * v; }
	v_pk_fma_f32 v[78:79], s[4:5], v[78:79], v[92:93] op_sel_hi:[0,1,1]
	v_pk_fma_f32 v[80:81], s[4:5], v[80:81], v[90:91] op_sel_hi:[0,1,1]
	v_pk_fma_f32 v[82:83], s[4:5], v[82:83], v[88:89] op_sel_hi:[0,1,1]
	v_pk_fma_f32 v[72:73], s[4:5], v[72:73], v[86:87] op_sel_hi:[0,1,1]
	v_readlane_b32 s4, v12, 2
	s_nop 1
	v_pk_fma_f32 v[4:5], s[4:5], v[84:85], v[4:5] op_sel_hi:[0,1,1]
	v_cvt_scalef32_pk_f32_fp4 v[84:85], v70, 1.0 op_sel:[1,0,0]
	v_pk_fma_f32 v[84:85], s[4:5], v[84:85], v[6:7] op_sel_hi:[0,1,1]
	v_cvt_scalef32_pk_f32_fp4 v[6:7], v70, 1.0 op_sel:[0,1,0]
	v_pk_fma_f32 v[90:91], s[4:5], v[6:7], v[74:75] op_sel_hi:[0,1,1]
	v_cvt_scalef32_pk_f32_fp4 v[6:7], v70, 1.0 op_sel:[1,1,0]
	v_pk_fma_f32 v[92:93], s[4:5], v[6:7], v[76:77] op_sel_hi:[0,1,1]
	v_cvt_scalef32_pk_f32_fp4 v[6:7], v71, 1.0
	v_pk_fma_f32 v[94:95], s[4:5], v[6:7], v[78:79] op_sel_hi:[0,1,1]
	v_cvt_scalef32_pk_f32_fp4 v[6:7], v71, 1.0 op_sel:[1,0,0]
	v_pk_fma_f32 v[96:97], s[4:5], v[6:7], v[80:81] op_sel_hi:[0,1,1]
	v_cvt_scalef32_pk_f32_fp4 v[6:7], v71, 1.0 op_sel:[0,1,0]
	v_pk_fma_f32 v[98:99], s[4:5], v[6:7], v[82:83] op_sel_hi:[0,1,1]
	v_cvt_scalef32_pk_f32_fp4 v[6:7], v71, 1.0 op_sel:[1,1,0]
	v_pk_fma_f32 v[100:101], s[4:5], v[6:7], v[72:73] op_sel_hi:[0,1,1]
	v_ashrrev_i32_e32 v6, 11, v8
	v_mul_i32_i24_e32 v6, 0x1800, v6
	v_ashrrev_i32_e32 v7, 31, v6
	v_lshl_add_u64 v[6:7], v[6:7], 2, s[22:23]
	v_readlane_b32 s4, v12, 1
	global_load_dwordx4 v[70:73], v[28:29], off offset:16
	global_load_dwordx4 v[74:77], v[28:29], off
	v_lshl_add_u64 v[28:29], v[6:7], 0, v[26:27]
	v_cvt_scalef32_pk_f32_fp4 v[82:83], v62, 1.0
	v_add_co_u32_e32 v6, vcc, s40, v28
	v_pk_fma_f32 v[104:105], s[4:5], v[82:83], v[4:5] op_sel_hi:[0,1,1]
	v_cvt_scalef32_pk_f32_fp4 v[4:5], v62, 1.0 op_sel:[1,0,0]
	v_addc_co_u32_e32 v7, vcc, 0, v29, vcc
	v_pk_fma_f32 v[106:107], s[4:5], v[4:5], v[84:85] op_sel_hi:[0,1,1]
	v_lshl_add_u64 v[4:5], v[28:29], 0, s[30:31]
	v_pk_fma_f32 v[28:29], s[4:5], v[108:109], v[90:91] op_sel_hi:[0,1,1]
	v_cvt_scalef32_pk_f32_fp4 v[90:91], v62, 1.0 op_sel:[1,1,0]
	v_pk_fma_f32 v[108:109], s[4:5], v[90:91], v[92:93] op_sel_hi:[0,1,1]
	v_cvt_scalef32_pk_f32_fp4 v[90:91], v63, 1.0
	global_load_dwordx4 v[78:81], v[6:7], off
	v_pk_fma_f32 v[94:95], s[4:5], v[90:91], v[94:95] op_sel_hi:[0,1,1]
	v_cvt_scalef32_pk_f32_fp4 v[90:91], v63, 1.0 op_sel:[1,0,0]
	global_load_dwordx4 v[82:85], v[4:5], off offset:32
	global_load_dwordx4 v[86:89], v[4:5], off offset:16
	v_pk_fma_f32 v[96:97], s[4:5], v[90:91], v[96:97] op_sel_hi:[0,1,1]
	v_cvt_scalef32_pk_f32_fp4 v[90:91], v63, 1.0 op_sel:[0,1,0]
	v_cvt_scalef32_pk_f32_fp4 v[62:63], v63, 1.0 op_sel:[1,1,0]
	v_pk_fma_f32 v[98:99], s[4:5], v[90:91], v[98:99] op_sel_hi:[0,1,1]
	v_pk_fma_f32 v[62:63], s[4:5], v[62:63], v[100:101] op_sel_hi:[0,1,1]
	v_readlane_b32 s4, v12, 3
	s_waitcnt vmcnt(11)
	v_cvt_scalef32_pk_f32_fp4 v[90:91], v58, 1.0
	v_mov_b32_e32 v12, v13
	v_pk_fma_f32 v[100:101], s[4:5], v[90:91], v[104:105] op_sel_hi:[0,1,1]
	global_load_dwordx4 v[90:93], v[4:5], off offset:48
	v_cvt_scalef32_pk_f32_fp4 v[104:105], v58, 1.0 op_sel:[1,0,0]
	v_pk_fma_f32 v[104:105], s[4:5], v[104:105], v[106:107] op_sel_hi:[0,1,1]
	v_cvt_scalef32_pk_f32_fp4 v[106:107], v58, 1.0 op_sel:[0,1,0]
	v_pk_fma_f32 v[28:29], s[4:5], v[106:107], v[28:29] op_sel_hi:[0,1,1]
	v_cvt_scalef32_pk_f32_fp4 v[106:107], v58, 1.0 op_sel:[1,1,0]
	v_pk_fma_f32 v[106:107], s[4:5], v[106:107], v[108:109] op_sel_hi:[0,1,1]
	v_cvt_scalef32_pk_f32_fp4 v[108:109], v59, 1.0
	v_pk_fma_f32 v[94:95], s[4:5], v[108:109], v[94:95] op_sel_hi:[0,1,1]
	v_cvt_scalef32_pk_f32_fp4 v[108:109], v59, 1.0 op_sel:[1,0,0]
	s_waitcnt vmcnt(9)
	v_dot8c_i32_i4_e32 v12, v64, v0
	v_dot8c_i32_i4_e32 v27, v64, v1
	v_pk_fma_f32 v[96:97], s[4:5], v[108:109], v[96:97] op_sel_hi:[0,1,1]
	v_cvt_scalef32_pk_f32_fp4 v[108:109], v59, 1.0 op_sel:[0,1,0]
	v_cvt_scalef32_pk_f32_fp4 v[58:59], v59, 1.0 op_sel:[1,1,0]
	v_dot8c_i32_i4_e32 v12, v65, v2
	v_dot8c_i32_i4_e32 v27, v65, v3
	v_pk_fma_f32 v[98:99], s[4:5], v[108:109], v[98:99] op_sel_hi:[0,1,1]
	v_pk_fma_f32 v[108:109], s[4:5], v[58:59], v[62:63] op_sel_hi:[0,1,1]
	v_mov_b32_e32 v58, v13
	v_lshl_add_u32 v12, v12, 4, v27
	v_mov_b32_e32 v27, v13
	v_dot8c_i32_i4_e32 v27, v68, v0
	v_dot8c_i32_i4_e32 v58, v68, v1
	v_dot8c_i32_i4_e32 v27, v69, v2
	v_dot8c_i32_i4_e32 v58, v69, v3
	v_mov_b32_e32 v59, v13
	s_waitcnt vmcnt(7)
	v_dot8c_i32_i4_e32 v59, v60, v1
	v_dot8c_i32_i4_e32 v59, v61, v3
	v_lshl_add_u32 v27, v27, 4, v58
	v_mov_b32_e32 v58, v13
	v_dot8c_i32_i4_e32 v58, v60, v0
	v_dot8c_i32_i4_e32 v58, v61, v2
	s_waitcnt vmcnt(4)
	v_lshlrev_b32_e32 v110, 16, v74
	s_nop 0
	v_lshl_add_u32 v58, v58, 4, v59
	v_mov_b32_e32 v59, v13
	v_dot8c_i32_i4_e32 v59, v66, v0
	v_mov_b32_e32 v0, v13
	v_dot8c_i32_i4_e32 v0, v66, v1
	v_dot8c_i32_i4_e32 v59, v67, v2
	v_dot8c_i32_i4_e32 v0, v67, v3
	v_cndmask_b32_e64 v2, v58, v12, s[0:1]
	v_and_b32_e32 v111, 0xffff0000, v74
	v_lshlrev_b32_e32 v74, 16, v75
	v_lshl_add_u32 v0, v59, 4, v0
	v_cndmask_b32_e64 v1, v27, v0, s[0:1]
	v_cndmask_b32_e64 v0, v0, v27, s[0:1]
	v_and_b32_e32 v75, 0xffff0000, v75
	s_waitcnt vmcnt(3)
	v_pk_fma_f32 v[74:75], v[104:105], v[80:81], v[74:75]
	v_add_u32_dpp v0, v0, v1 quad_perm:[1,0,3,2] row_mask:0xf bank_mask:0xf bound_ctrl:1
	v_cndmask_b32_e64 v1, v12, v58, s[0:1]
	v_lshlrev_b32_e32 v104, 16, v76
	v_and_b32_e32 v105, 0xffff0000, v76
	v_add_u32_dpp v1, v2, v1 quad_perm:[1,0,3,2] row_mask:0xf bank_mask:0xf bound_ctrl:1
	v_cndmask_b32_e64 v12, v1, v0, s[2:3]
	v_cndmask_b32_e64 v27, v0, v1, s[2:3]
	global_load_dwordx4 v[0:3], v[24:25], off offset:48
	global_load_dwordx4 v[58:61], v[24:25], off offset:32
	global_load_dwordx4 v[62:65], v[24:25], off offset:16
	global_load_dwordx4 v[66:69], v[24:25], off
	v_pk_fma_f32 v[78:79], v[100:101], v[78:79], v[110:111]
	s_waitcnt vmcnt(5)
; __device__ __forceinline__ float bf_lo(unsigned u) { return __uint_as_float(u << 16); }
; __device__ __forceinline__ float bf_hi(unsigned u) { return __uint_as_float(u & 0xffff0000u); }
; __device__ __forceinline__ void p3_finish(const Params& p, float* dstp, int tok, int lane, const f32x2 (&acc)[8], float* tr) {
;     const float* mod = (const float*)(p.ws + OFF_MOD);
;     const int b = tok >> 11;
;     float own[16];
; #pragma unroll
;     for (int i = 0; i < 16; i++) own[i] = acc[i >> 1][i & 1];
;     const int d0 = lane * 16;
;     float x2[16];
;     float ss = 0.f;
;     const bf16_t* x1b = (const bf16_t*)(p.ws + OFF_X1B) + (size_t)tok * DM + d0;
;     const u32x4 xa = *(const u32x4*)x1b, xb = *(const u32x4*)(x1b + 8);
;     const unsigned xw[8] = {xa.x, xa.y, xa.z, xa.w, xb.x, xb.y, xb.z, xb.w};
; #pragma unroll
;     for (int i = 0; i < 4; i++) {
;         const int d = d0 + i * 4;
;         const f32x4 xv = {bf_lo(xw[2 * i]), bf_hi(xw[2 * i]), bf_lo(xw[2 * i + 1]), bf_hi(xw[2 * i + 1])};
;         const f32x4 gt = *(const f32x4*)(mod + b * 6144 + 5 * 1024 + d);
; #pragma unroll
;         for (int j = 0; j < 4; j++) { const float v = xv[j] + gt[j] * own[i * 4 + j]; x2[i * 4 + j] = v; ss += v * v; }
;     }
;     ss = wave_sum(ss);
;     const float rstd = rsqrtf(ss * (1.f / 1024.f) + 1e-6f);
; #pragma unroll
;     for (int i = 0; i < 4; i++) {
;         const int d = d0 + i * 4;
;         const f32x4 fg = *(const f32x4*)(p.final_g + d);
;         f32x4 o;
; #pragma unroll
;         for (int j = 0; j < 4; j++) o[j] = x2[i * 4 + j] * rstd * fg[j];
;         *(f32x4*)(tr + d) = o;
;     }
;     __builtin_amdgcn_fence(__ATOMIC_RELEASE, "wavefront");
;     __builtin_amdgcn_wave_barrier();
;     __builtin_amdgcn_fence(__ATOMIC_ACQUIRE, "wavefront");
; #pragma unroll
;     for (int j = 0; j < 4; j++) {
;         const f32x4 v = *(const f32x4*)(tr + j * 256 + lane * 4);
;         *(f32x4*)(dstp + (size_t)tok * DM + j * 256 + lane * 4) = v;
;     }
;     __builtin_amdgcn_wave_barrier();
; }
	v_pk_fma_f32 v[28:29], v[28:29], v[86:87], v[104:105]
	v_lshlrev_b32_e32 v104, 16, v70
	v_and_b32_e32 v105, 0xffff0000, v70
	v_lshlrev_b32_e32 v70, 16, v71
	v_and_b32_e32 v71, 0xffff0000, v71
	v_pk_mul_f32 v[100:101], v[78:79], v[78:79]
	v_pk_fma_f32 v[70:71], v[96:97], v[84:85], v[70:71]
	v_lshlrev_b32_e32 v96, 16, v72
	v_and_b32_e32 v97, 0xffff0000, v72
	v_pk_mul_f32 v[80:81], v[74:75], v[74:75]
	s_waitcnt vmcnt(4)
	v_pk_fma_f32 v[90:91], v[98:99], v[90:91], v[96:97]
	v_add_f32_e32 v98, v100, v101
	v_add_f32_e32 v80, v80, v98
	v_pk_mul_f32 v[86:87], v[28:29], v[28:29]
	v_lshlrev_b32_e32 v76, 16, v77
	v_and_b32_e32 v77, 0xffff0000, v77
	v_add_f32_e32 v80, v81, v80
	v_pk_fma_f32 v[76:77], v[106:107], v[88:89], v[76:77]
	v_add_f32_e32 v80, v86, v80
	v_pk_mul_f32 v[88:89], v[76:77], v[76:77]
	v_add_f32_e32 v80, v87, v80
	v_pk_fma_f32 v[82:83], v[94:95], v[82:83], v[104:105]
	v_add_f32_e32 v80, v88, v80
	v_pk_mul_f32 v[94:95], v[82:83], v[82:83]
	v_add_f32_e32 v80, v89, v80
	v_add_f32_e32 v80, v94, v80
	v_pk_mul_f32 v[84:85], v[70:71], v[70:71]
	v_add_f32_e32 v80, v95, v80
	v_add_f32_e32 v80, v84, v80
	v_pk_mul_f32 v[96:97], v[90:91], v[90:91]
	v_lshlrev_b32_e32 v72, 16, v73
	v_and_b32_e32 v73, 0xffff0000, v73
	v_add_f32_e32 v80, v85, v80
	v_pk_fma_f32 v[72:73], v[108:109], v[92:93], v[72:73]
	v_add_f32_e32 v80, v96, v80
	v_pk_mul_f32 v[92:93], v[72:73], v[72:73]
	v_add_f32_e32 v80, v97, v80
	v_add_f32_e32 v80, v92, v80
	v_add_f32_e32 v80, v93, v80
	ds_bpermute_b32 v81, v112, v80
	v_add_u32_dpp v12, v27, v12 quad_perm:[2,3,0,1] row_mask:0xf bank_mask:0xf bound_ctrl:1
	s_waitcnt lgkmcnt(0)
	v_add_f32_e32 v80, v80, v81
	ds_bpermute_b32 v81, v113, v80
	v_add_u32_dpp v12, v12, v12 row_ror:4 row_mask:0xf bank_mask:0xf bound_ctrl:1
	s_waitcnt lgkmcnt(0)
	v_add_f32_e32 v80, v80, v81
	v_add_u32_dpp v12, v12, v12 row_ror:8 row_mask:0xf bank_mask:0xf bound_ctrl:1
	v_mov_b32_e32 v27, v12
	ds_bpermute_b32 v81, v114, v80
	s_nop 0
	v_permlane16_swap_b32_e32 v12, v27
	v_add_u32_e32 v12, v12, v27
	v_mov_b32_e32 v27, v12
	s_nop 1
	v_permlane32_swap_b32_e32 v12, v27
	v_add_u32_e32 v12, v27, v12
	s_waitcnt lgkmcnt(0)
	v_add_f32_e32 v27, v80, v81
	ds_bpermute_b32 v80, v115, v27
	v_cvt_f32_i32_e32 v12, v12
	s_waitcnt lgkmcnt(0)
	v_add_f32_e32 v27, v27, v80
	ds_bpermute_b32 v80, v116, v27
	v_mul_f32_e32 v81, v103, v12
	v_fma_f32 v12, |v81|, s39, 1.0
	v_rcp_f32_e32 v12, v12
	s_waitcnt lgkmcnt(0)
	v_add_f32_e32 v27, v27, v80
	ds_bpermute_b32 v80, v117, v27
	v_fmamk_f32 v84, v12, 0x3f07dc22, v129
	v_fmaak_f32 v84, v12, v84, 0x3f35f0e3
	v_fmaak_f32 v84, v12, v84, 0xbe11a98e
	v_fmaak_f32 v84, v12, v84, 0x3e027906
	s_waitcnt lgkmcnt(0)
	v_add_f32_e32 v27, v27, v80
	v_mul_f32_e32 v12, v12, v84
	v_mul_f32_e32 v84, v81, v81
	v_fmamk_f32 v27, v27, 0x3a800000, v130
	v_mul_f32_e32 v84, 0xbf38aa3b, v84
	v_mul_f32_e32 v80, 0x4b800000, v27
	v_cmp_gt_f32_e32 vcc, s38, v27
	v_exp_f32_e32 v84, v84
	s_nop 0
	v_cndmask_b32_e32 v27, v27, v80, vcc
	v_rsq_f32_e32 v27, v27
	v_mul_f32_e32 v12, v84, v12
	v_mul_f32_e32 v80, v81, v12
	v_fma_f32 v84, -v81, v12, v81
	v_mul_f32_e32 v12, 0x45800000, v27
	v_cndmask_b32_e32 v12, v27, v12, vcc
	v_pk_mul_f32 v[78:79], v[78:79], v[12:13] op_sel_hi:[1,0]
	v_pk_mul_f32 v[74:75], v[74:75], v[12:13] op_sel_hi:[1,0]
	s_waitcnt vmcnt(0)
	v_pk_mul_f32 v[66:67], v[66:67], v[78:79]
	v_pk_mul_f32 v[68:69], v[68:69], v[74:75]
	ds_write_b128 v118, v[66:69]
	v_pk_mul_f32 v[28:29], v[28:29], v[12:13] op_sel_hi:[1,0]
	v_pk_mul_f32 v[66:67], v[76:77], v[12:13] op_sel_hi:[1,0]
	v_pk_mul_f32 v[62:63], v[62:63], v[28:29]
	v_pk_mul_f32 v[64:65], v[64:65], v[66:67]
	ds_write_b128 v118, v[62:65] offset:16
	v_pk_mul_f32 v[28:29], v[82:83], v[12:13] op_sel_hi:[1,0]
	v_pk_mul_f32 v[62:63], v[70:71], v[12:13] op_sel_hi:[1,0]
	v_pk_mul_f32 v[58:59], v[58:59], v[28:29]
	v_pk_mul_f32 v[60:61], v[60:61], v[62:63]
	ds_write_b128 v118, v[58:61] offset:32
	v_pk_mul_f32 v[28:29], v[90:91], v[12:13] op_sel_hi:[1,0]
	v_pk_mul_f32 v[58:59], v[72:73], v[12:13] op_sel_hi:[1,0]
	v_pk_mul_f32 v[0:1], v[0:1], v[28:29]
	v_pk_mul_f32 v[2:3], v[2:3], v[58:59]
	ds_write_b128 v118, v[0:3] offset:48
	ds_read_b128 v[0:3], v128
	ds_read_b128 v[58:61], v128 offset:1024
	ds_read_b128 v[62:65], v128 offset:2048
	ds_read_b128 v[66:69], v128 offset:3072
	v_lshlrev_b64 v[28:29], 12, v[8:9]
	v_lshl_add_u64 v[28:29], v[18:19], 0, v[28:29]
	s_waitcnt lgkmcnt(3)
	global_store_dwordx4 v[28:29], v[0:3], off
	s_waitcnt lgkmcnt(2)
	global_store_dwordx4 v[28:29], v[58:61], off offset:1024
	s_waitcnt lgkmcnt(1)
	global_store_dwordx4 v[28:29], v[62:65], off offset:2048
	s_waitcnt lgkmcnt(0)
	global_store_dwordx4 v[28:29], v[66:69], off offset:3072
	v_lshl_add_u64 v[28:29], v[22:23], 0, v[32:33]
	global_load_dwordx4 v[0:3], v[28:29], off offset:16
	global_load_dwordx4 v[58:61], v[28:29], off
	global_load_dwordx4 v[62:65], v[6:7], off
	v_cmp_gt_f32_e32 vcc, 0, v81
	global_load_dwordx4 v[66:69], v[4:5], off offset:32
	global_load_dwordx4 v[70:73], v[4:5], off offset:16
	v_cndmask_b32_e32 v6, v84, v80, vcc
	v_mul_f32_e32 v9, v102, v6
	v_cvt_scalef32_pk_f32_fp4 v[6:7], v40, 1.0
	v_readlane_b32 s4, v9, 0
	v_add_u32_e32 v8, s36, v8
	s_waitcnt vmcnt(3)
; __device__ __forceinline__ float bf_lo(unsigned u) { return __uint_as_float(u << 16); }
; __device__ __forceinline__ float bf_hi(unsigned u) { return __uint_as_float(u & 0xffff0000u); }
; __device__ __forceinline__ void p3_axpy(const u32x2 (&vr)[4], float ws, f32x2 (&acc)[8]) {
; #pragma unroll
;     for (int u = 0; u < 4; u++) {
;         const int la = ((u >> 1) & 1) | ((u & 1) << 1);
;         const float wu = __builtin_bit_cast(float, __builtin_amdgcn_readlane(__builtin_bit_cast(int, ws), la));
;         const f32x2 w2 = {wu, wu};
;         const unsigned vw[2] = {vr[u].x, vr[u].y};
; #pragma unroll
;         for (int i = 0; i < 2; i++) {
;             acc[i * 4 + 0] = __builtin_elementwise_fma(w2, __builtin_amdgcn_cvt_scalef32_pk_f32_fp4(vw[i], 1.0f, 0), acc[i * 4 + 0]);
;             acc[i * 4 + 1] = __builtin_elementwise_fma(w2, __builtin_amdgcn_cvt_scalef32_pk_f32_fp4(vw[i], 1.0f, 1), acc[i * 4 + 1]);
;             acc[i * 4 + 2] = __builtin_elementwise_fma(w2, __builtin_amdgcn_cvt_scalef32_pk_f32_fp4(vw[i], 1.0f, 2), acc[i * 4 + 2]);
;             acc[i * 4 + 3] = __builtin_elementwise_fma(w2, __builtin_amdgcn_cvt_scalef32_pk_f32_fp4(vw[i], 1.0f, 3), acc[i * 4 + 3]);
;         }
;     }
; }
; __device__ __forceinline__ void p3_finish(const Params& p, float* dstp, int tok, int lane, const f32x2 (&acc)[8], float* tr) {
;     ...
;     const bf16_t* x1b = (const bf16_t*)(p.ws + OFF_X1B) + (size_t)tok * DM + d0;
;     const u32x4 xa = *(const u32x4*)x1b, xb = *(const u32x4*)(x1b + 8);
;     const unsigned xw[8] = {xa.x, xa.y, xa.z, xa.w, xb.x, xb.y, xb.z, xb.w};
; #pragma unroll
;     for (int i = 0; i < 4; i++) {
;         const int d = d0 + i * 4;
;         const f32x4 xv = {bf_lo(xw[2 * i]), bf_hi(xw[2 * i]), bf_lo(xw[2 * i + 1]), bf_hi(xw[2 * i + 1])};
;         const f32x4 gt = *(const f32x4*)(mod + b * 6144 + 5 * 1024 + d);
	v_lshlrev_b32_e32 v78, 16, v58
	v_pk_fma_f32 v[28:29], s[4:5], v[6:7], v[52:53] op_sel_hi:[0,1,1]
	v_cvt_scalef32_pk_f32_fp4 v[6:7], v40, 1.0 op_sel:[1,0,0]
	v_pk_fma_f32 v[32:33], s[4:5], v[6:7], v[50:51] op_sel_hi:[0,1,1]
	v_cvt_scalef32_pk_f32_fp4 v[6:7], v40, 1.0 op_sel:[0,1,0]
	v_pk_fma_f32 v[48:49], s[4:5], v[6:7], v[48:49] op_sel_hi:[0,1,1]
	v_cvt_scalef32_pk_f32_fp4 v[6:7], v40, 1.0 op_sel:[1,1,0]
	v_pk_fma_f32 v[46:47], s[4:5], v[6:7], v[46:47] op_sel_hi:[0,1,1]
	v_cvt_scalef32_pk_f32_fp4 v[6:7], v41, 1.0
	v_pk_fma_f32 v[44:45], s[4:5], v[6:7], v[44:45] op_sel_hi:[0,1,1]
	v_cvt_scalef32_pk_f32_fp4 v[6:7], v41, 1.0 op_sel:[1,0,0]
	v_pk_fma_f32 v[42:43], s[4:5], v[6:7], v[42:43] op_sel_hi:[0,1,1]
	v_cvt_scalef32_pk_f32_fp4 v[6:7], v41, 1.0 op_sel:[0,1,0]
	v_pk_fma_f32 v[50:51], s[4:5], v[6:7], v[54:55] op_sel_hi:[0,1,1]
	v_cvt_scalef32_pk_f32_fp4 v[6:7], v41, 1.0 op_sel:[1,1,0]
	v_pk_fma_f32 v[40:41], s[4:5], v[6:7], v[56:57] op_sel_hi:[0,1,1]
	global_load_dwordx4 v[4:7], v[4:5], off offset:48
	v_readlane_b32 s4, v9, 2
	v_cvt_scalef32_pk_f32_fp4 v[52:53], v38, 1.0
	v_and_b32_e32 v79, 0xffff0000, v58
	v_pk_fma_f32 v[28:29], s[4:5], v[52:53], v[28:29] op_sel_hi:[0,1,1]
	v_cvt_scalef32_pk_f32_fp4 v[52:53], v38, 1.0 op_sel:[1,0,0]
	v_pk_fma_f32 v[32:33], s[4:5], v[52:53], v[32:33] op_sel_hi:[0,1,1]
	v_cvt_scalef32_pk_f32_fp4 v[52:53], v38, 1.0 op_sel:[0,1,0]
	v_pk_fma_f32 v[48:49], s[4:5], v[52:53], v[48:49] op_sel_hi:[0,1,1]
	v_cvt_scalef32_pk_f32_fp4 v[52:53], v38, 1.0 op_sel:[1,1,0]
	v_pk_fma_f32 v[46:47], s[4:5], v[52:53], v[46:47] op_sel_hi:[0,1,1]
	v_cvt_scalef32_pk_f32_fp4 v[52:53], v39, 1.0
	v_pk_fma_f32 v[44:45], s[4:5], v[52:53], v[44:45] op_sel_hi:[0,1,1]
	v_cvt_scalef32_pk_f32_fp4 v[52:53], v39, 1.0 op_sel:[1,0,0]
	v_pk_fma_f32 v[42:43], s[4:5], v[52:53], v[42:43] op_sel_hi:[0,1,1]
	v_cvt_scalef32_pk_f32_fp4 v[52:53], v39, 1.0 op_sel:[0,1,0]
	v_cvt_scalef32_pk_f32_fp4 v[38:39], v39, 1.0 op_sel:[1,1,0]
	v_pk_fma_f32 v[50:51], s[4:5], v[52:53], v[50:51] op_sel_hi:[0,1,1]
	v_pk_fma_f32 v[38:39], s[4:5], v[38:39], v[40:41] op_sel_hi:[0,1,1]
	v_readlane_b32 s4, v9, 1
	v_cvt_scalef32_pk_f32_fp4 v[40:41], v36, 1.0
	v_lshlrev_b32_e32 v58, 16, v59
	v_pk_fma_f32 v[28:29], s[4:5], v[40:41], v[28:29] op_sel_hi:[0,1,1]
	v_cvt_scalef32_pk_f32_fp4 v[40:41], v36, 1.0 op_sel:[1,0,0]
	v_pk_fma_f32 v[32:33], s[4:5], v[40:41], v[32:33] op_sel_hi:[0,1,1]
	v_cvt_scalef32_pk_f32_fp4 v[40:41], v36, 1.0 op_sel:[0,1,0]
	v_pk_fma_f32 v[40:41], s[4:5], v[40:41], v[48:49] op_sel_hi:[0,1,1]
	v_cvt_scalef32_pk_f32_fp4 v[48:49], v36, 1.0 op_sel:[1,1,0]
	v_pk_fma_f32 v[46:47], s[4:5], v[48:49], v[46:47] op_sel_hi:[0,1,1]
	v_cvt_scalef32_pk_f32_fp4 v[48:49], v37, 1.0
	v_pk_fma_f32 v[44:45], s[4:5], v[48:49], v[44:45] op_sel_hi:[0,1,1]
	v_cvt_scalef32_pk_f32_fp4 v[48:49], v37, 1.0 op_sel:[1,0,0]
	v_pk_fma_f32 v[42:43], s[4:5], v[48:49], v[42:43] op_sel_hi:[0,1,1]
	v_cvt_scalef32_pk_f32_fp4 v[48:49], v37, 1.0 op_sel:[0,1,0]
	v_cvt_scalef32_pk_f32_fp4 v[36:37], v37, 1.0 op_sel:[1,1,0]
	v_pk_fma_f32 v[48:49], s[4:5], v[48:49], v[50:51] op_sel_hi:[0,1,1]
	v_pk_fma_f32 v[36:37], s[4:5], v[36:37], v[38:39] op_sel_hi:[0,1,1]
	v_readlane_b32 s4, v9, 3
	v_cvt_scalef32_pk_f32_fp4 v[38:39], v34, 1.0
	v_and_b32_e32 v59, 0xffff0000, v59
	v_pk_fma_f32 v[28:29], s[4:5], v[38:39], v[28:29] op_sel_hi:[0,1,1]
	v_cvt_scalef32_pk_f32_fp4 v[38:39], v34, 1.0 op_sel:[1,0,0]
	v_pk_fma_f32 v[50:51], s[4:5], v[38:39], v[32:33] op_sel_hi:[0,1,1]
	v_cvt_scalef32_pk_f32_fp4 v[32:33], v34, 1.0 op_sel:[0,1,0]
	v_pk_fma_f32 v[52:53], s[4:5], v[32:33], v[40:41] op_sel_hi:[0,1,1]
	v_cvt_scalef32_pk_f32_fp4 v[32:33], v34, 1.0 op_sel:[1,1,0]
	v_pk_fma_f32 v[54:55], s[4:5], v[32:33], v[46:47] op_sel_hi:[0,1,1]
	v_cvt_scalef32_pk_f32_fp4 v[32:33], v35, 1.0
	v_pk_fma_f32 v[56:57], s[4:5], v[32:33], v[44:45] op_sel_hi:[0,1,1]
	v_cvt_scalef32_pk_f32_fp4 v[32:33], v35, 1.0 op_sel:[1,0,0]
	v_pk_fma_f32 v[74:75], s[4:5], v[32:33], v[42:43] op_sel_hi:[0,1,1]
	v_cvt_scalef32_pk_f32_fp4 v[32:33], v35, 1.0 op_sel:[0,1,0]
	v_pk_fma_f32 v[48:49], s[4:5], v[32:33], v[48:49] op_sel_hi:[0,1,1]
	v_cvt_scalef32_pk_f32_fp4 v[32:33], v35, 1.0 op_sel:[1,1,0]
	v_pk_fma_f32 v[76:77], s[4:5], v[32:33], v[36:37] op_sel_hi:[0,1,1]
	global_load_dwordx4 v[32:35], v[24:25], off offset:48
	global_load_dwordx4 v[36:39], v[24:25], off offset:32
	global_load_dwordx4 v[40:43], v[24:25], off offset:16
	global_load_dwordx4 v[44:47], v[24:25], off
	s_waitcnt vmcnt(7)
; __device__ __forceinline__ float bf_lo(unsigned u) { return __uint_as_float(u << 16); }
; __device__ __forceinline__ float bf_hi(unsigned u) { return __uint_as_float(u & 0xffff0000u); }
; __device__ __forceinline__ void p3_finish(const Params& p, float* dstp, int tok, int lane, const f32x2 (&acc)[8], float* tr) {
;     ...
; #pragma unroll
;     for (int i = 0; i < 4; i++) {
;         const int d = d0 + i * 4;
;         const f32x4 xv = {bf_lo(xw[2 * i]), bf_hi(xw[2 * i]), bf_lo(xw[2 * i + 1]), bf_hi(xw[2 * i + 1])};
;         const f32x4 gt = *(const f32x4*)(mod + b * 6144 + 5 * 1024 + d);
; #pragma unroll
;         for (int j = 0; j < 4; j++) { const float v = xv[j] + gt[j] * own[i * 4 + j]; x2[i * 4 + j] = v; ss += v * v; }
;     }
;     ss = wave_sum(ss);
;     const float rstd = rsqrtf(ss * (1.f / 1024.f) + 1e-6f);
; #pragma unroll
;     for (int i = 0; i < 4; i++) {
;         const int d = d0 + i * 4;
;         const f32x4 fg = *(const f32x4*)(p.final_g + d);
;         f32x4 o;
; #pragma unroll
;         for (int j = 0; j < 4; j++) o[j] = x2[i * 4 + j] * rstd * fg[j];
;         *(f32x4*)(tr + d) = o;
;     }
;     __builtin_amdgcn_fence(__ATOMIC_RELEASE, "wavefront");
;     __builtin_amdgcn_wave_barrier();
;     __builtin_amdgcn_fence(__ATOMIC_ACQUIRE, "wavefront");
; #pragma unroll
;     for (int j = 0; j < 4; j++) {
;         const f32x4 v = *(const f32x4*)(tr + j * 256 + lane * 4);
;         *(f32x4*)(dstp + (size_t)tok * DM + j * 256 + lane * 4) = v;
;     }
;     __builtin_amdgcn_wave_barrier();
; }
	v_pk_fma_f32 v[28:29], v[28:29], v[62:63], v[78:79]
	v_pk_fma_f32 v[50:51], v[50:51], v[64:65], v[58:59]
	v_pk_mul_f32 v[62:63], v[28:29], v[28:29]
	v_pk_mul_f32 v[58:59], v[50:51], v[50:51]
	v_lshlrev_b32_e32 v64, 16, v60
	v_and_b32_e32 v65, 0xffff0000, v60
	v_add_f32_e32 v9, v62, v63
	s_waitcnt vmcnt(5)
	v_pk_fma_f32 v[52:53], v[52:53], v[70:71], v[64:65]
	v_add_f32_e32 v9, v58, v9
	v_pk_mul_f32 v[64:65], v[52:53], v[52:53]
	v_lshlrev_b32_e32 v60, 16, v61
	v_and_b32_e32 v61, 0xffff0000, v61
	v_add_f32_e32 v9, v59, v9
	v_pk_fma_f32 v[54:55], v[54:55], v[72:73], v[60:61]
	v_add_f32_e32 v9, v64, v9
	v_pk_mul_f32 v[60:61], v[54:55], v[54:55]
	v_lshlrev_b32_e32 v70, 16, v0
	v_and_b32_e32 v71, 0xffff0000, v0
	v_add_f32_e32 v9, v65, v9
	v_pk_fma_f32 v[56:57], v[56:57], v[66:67], v[70:71]
	v_add_f32_e32 v9, v60, v9
	v_pk_mul_f32 v[66:67], v[56:57], v[56:57]
	v_lshlrev_b32_e32 v0, 16, v1
	v_and_b32_e32 v1, 0xffff0000, v1
	v_add_f32_e32 v9, v61, v9
	v_pk_fma_f32 v[68:69], v[74:75], v[68:69], v[0:1]
	v_add_f32_e32 v9, v66, v9
	v_pk_mul_f32 v[0:1], v[68:69], v[68:69]
	v_lshlrev_b32_e32 v70, 16, v2
	v_and_b32_e32 v71, 0xffff0000, v2
	v_add_f32_e32 v9, v67, v9
	s_waitcnt vmcnt(4)
	v_pk_fma_f32 v[4:5], v[48:49], v[4:5], v[70:71]
	v_add_f32_e32 v0, v0, v9
	v_pk_mul_f32 v[48:49], v[4:5], v[4:5]
	v_lshlrev_b32_e32 v2, 16, v3
	v_and_b32_e32 v3, 0xffff0000, v3
	v_add_f32_e32 v0, v1, v0
	v_pk_fma_f32 v[6:7], v[76:77], v[6:7], v[2:3]
	v_add_f32_e32 v0, v48, v0
	v_pk_mul_f32 v[2:3], v[6:7], v[6:7]
	v_add_f32_e32 v0, v49, v0
	v_add_f32_e32 v0, v2, v0
	v_add_f32_e32 v0, v3, v0
	s_nop 1
	v_add_f32_dpp v0, v0, v0 row_ror:8 row_mask:0xf bank_mask:0xf
	s_nop 1
	v_add_f32_dpp v0, v0, v0 row_ror:4 row_mask:0xf bank_mask:0xf
	s_nop 1
	v_add_f32_dpp v0, v0, v0 row_ror:2 row_mask:0xf bank_mask:0xf
	s_nop 1
	v_add_f32_dpp v0, v0, v0 row_ror:1 row_mask:0xf bank_mask:0xf
	v_mov_b32_e32 v1, v0
	s_nop 1
	v_permlane16_swap_b32_e32 v0, v1
	v_add_f32_e32 v0, v0, v1
	v_mov_b32_e32 v1, v0
	s_nop 1
	v_permlane32_swap_b32_e32 v0, v1
	v_add_f32_e32 v0, v0, v1
	v_fmamk_f32 v0, v0, 0x3a800000, v130
	v_mul_f32_e32 v1, 0x4b800000, v0
	v_cmp_gt_f32_e32 vcc, s38, v0
	s_nop 1
	v_cndmask_b32_e32 v0, v0, v1, vcc
	v_rsq_f32_e32 v0, v0
	s_nop 0
	v_mul_f32_e32 v1, 0x45800000, v0
	v_cndmask_b32_e32 v12, v0, v1, vcc
	v_pk_mul_f32 v[0:1], v[28:29], v[12:13] op_sel_hi:[1,0]
	v_pk_mul_f32 v[2:3], v[50:51], v[12:13] op_sel_hi:[1,0]
	s_waitcnt vmcnt(0)
	v_pk_mul_f32 v[0:1], v[44:45], v[0:1]
	v_pk_mul_f32 v[2:3], v[46:47], v[2:3]
	ds_write_b128 v118, v[0:3]
	v_pk_mul_f32 v[0:1], v[52:53], v[12:13] op_sel_hi:[1,0]
	v_pk_mul_f32 v[2:3], v[54:55], v[12:13] op_sel_hi:[1,0]
	v_pk_mul_f32 v[0:1], v[40:41], v[0:1]
	v_pk_mul_f32 v[2:3], v[42:43], v[2:3]
	ds_write_b128 v118, v[0:3] offset:16
	v_pk_mul_f32 v[0:1], v[56:57], v[12:13] op_sel_hi:[1,0]
	v_pk_mul_f32 v[2:3], v[68:69], v[12:13] op_sel_hi:[1,0]
	v_pk_mul_f32 v[0:1], v[36:37], v[0:1]
	v_pk_mul_f32 v[2:3], v[38:39], v[2:3]
	ds_write_b128 v118, v[0:3] offset:32
	v_pk_mul_f32 v[0:1], v[4:5], v[12:13] op_sel_hi:[1,0]
	v_pk_mul_f32 v[2:3], v[6:7], v[12:13] op_sel_hi:[1,0]
	v_pk_mul_f32 v[0:1], v[32:33], v[0:1]
	v_pk_mul_f32 v[2:3], v[34:35], v[2:3]
	ds_write_b128 v118, v[0:3] offset:48
	ds_read_b128 v[0:3], v128
	ds_read_b128 v[4:7], v128 offset:1024
	v_lshlrev_b64 v[32:33], 12, v[30:31]
	v_lshl_add_u64 v[32:33], v[18:19], 0, v[32:33]
	ds_read_b128 v[28:31], v128 offset:2048
	s_waitcnt lgkmcnt(2)
	global_store_dwordx4 v[32:33], v[0:3], off
	s_waitcnt lgkmcnt(1)
	global_store_dwordx4 v[32:33], v[4:7], off offset:1024
	ds_read_b128 v[0:3], v128 offset:3072
	v_cmp_lt_i32_e32 vcc, s41, v8
	s_or_b64 s[28:29], vcc, s[28:29]
	s_waitcnt lgkmcnt(1)
	global_store_dwordx4 v[32:33], v[28:31], off offset:2048
	s_waitcnt lgkmcnt(0)
	global_store_dwordx4 v[32:33], v[0:3], off offset:3072
	s_andn2_b64 exec, exec, s[28:29]
	s_cbranch_execnz .LBB0_1042
